# solve block prefetch depth tuned (lead 10, max 6 outstanding)
# speedup vs baseline: 1.1479x; 1.0008x over previous
.LBB0_601:
	s_mov_b64 s[16:17], src_shared_base
	s_cmp_lg_u32 16, -1
	s_cselect_b32 s16, 16, 0
	s_cselect_b32 s17, s17, 0
	s_add_u32 s16, s16, 0x11b80
	s_addc_u32 s17, s17, 0
	s_cmp_lg_u64 s[16:17], 0
	s_cselect_b32 s16, s16, -1
	s_add_i32 s17, 16, 0x11980
	v_mov_b32_e32 v60, s17
	v_mov_b32_e32 v61, s16
	v_cndmask_b32_e64 v60, v60, v61, s[20:21]
	ds_read2_b32 v[60:61], v60 offset1:1
	s_add_i32 s17, s16, 8
	s_add_i32 s18, 16, 0x11988
	v_mov_b32_e32 v62, s18
	v_mov_b32_e32 v63, s17
	v_cndmask_b32_e64 v62, v62, v63, s[20:21]
	s_add_i32 s17, s16, 16
	s_add_i32 s18, 16, 0x11990
	ds_read2_b32 v[66:67], v62 offset1:1
	v_mov_b32_e32 v62, s18
	v_mov_b32_e32 v63, s17
	v_cndmask_b32_e64 v62, v62, v63, s[20:21]
	s_add_i32 s17, s16, 24
	s_add_i32 s18, 16, 0x11998
	s_waitcnt lgkmcnt(1)
	v_pk_mul_f32 v[60:61], v[122:123], v[60:61]
	ds_read2_b32 v[122:123], v62 offset1:1
	v_mov_b32_e32 v62, s18
	v_mov_b32_e32 v63, s17
	v_cndmask_b32_e64 v62, v62, v63, s[20:21]
	s_add_i32 s17, s16, 32
	s_add_i32 s18, 16, 0x119a0
	ds_read2_b32 v[200:201], v62 offset1:1
	v_mov_b32_e32 v62, s18
	v_mov_b32_e32 v63, s17
	v_cndmask_b32_e64 v62, v62, v63, s[20:21]
	s_add_i32 s17, s16, 40
	s_add_i32 s18, 16, 0x119a8
	ds_read2_b32 v[202:203], v62 offset1:1
	v_mov_b32_e32 v62, s18
	v_mov_b32_e32 v63, s17
	v_cndmask_b32_e64 v62, v62, v63, s[20:21]
	s_add_i32 s17, s16, 48
	s_add_i32 s18, 16, 0x119b0
	ds_read2_b32 v[204:205], v62 offset1:1
	v_mov_b32_e32 v62, s18
	v_mov_b32_e32 v63, s17
	v_cndmask_b32_e64 v62, v62, v63, s[20:21]
	s_add_i32 s17, s16, 56
	s_add_i32 s18, 16, 0x119b8
	ds_read2_b32 v[206:207], v62 offset1:1
	v_mov_b32_e32 v62, s18
	v_mov_b32_e32 v63, s17
	v_cndmask_b32_e64 v62, v62, v63, s[20:21]
	s_add_i32 s17, s16, 64
	s_add_i32 s18, 16, 0x119c0
	ds_read2_b32 v[208:209], v62 offset1:1
	v_mov_b32_e32 v62, s18
	v_mov_b32_e32 v63, s17
	v_cndmask_b32_e64 v62, v62, v63, s[20:21]
	s_add_i32 s17, s16, 0x48
	s_add_i32 s18, 16, 0x119c8
	ds_read2_b32 v[210:211], v62 offset1:1
	v_mov_b32_e32 v62, s18
	v_mov_b32_e32 v63, s17
	v_cndmask_b32_e64 v62, v62, v63, s[20:21]
	s_add_i32 s17, s16, 0x50
	s_add_i32 s18, 16, 0x119d0
	ds_read2_b32 v[212:213], v62 offset1:1
	v_mov_b32_e32 v62, s18
	v_mov_b32_e32 v63, s17
	v_cndmask_b32_e64 v62, v62, v63, s[20:21]
	s_add_i32 s17, s16, 0x58
	s_add_i32 s18, 16, 0x119d8
	ds_read2_b32 v[214:215], v62 offset1:1
	v_mov_b32_e32 v62, s18
	v_mov_b32_e32 v63, s17
	v_cndmask_b32_e64 v62, v62, v63, s[20:21]
	s_add_i32 s17, s16, 0x60
	s_add_i32 s18, 16, 0x119e0
	ds_read2_b32 v[216:217], v62 offset1:1
	v_mov_b32_e32 v62, s18
	v_mov_b32_e32 v63, s17
	v_cndmask_b32_e64 v62, v62, v63, s[20:21]
	s_add_i32 s17, s16, 0x68
	s_add_i32 s18, 16, 0x119e8
	ds_read2_b32 v[218:219], v62 offset1:1
	v_mov_b32_e32 v62, s18
	v_mov_b32_e32 v63, s17
	s_add_i32 s17, s16, 0x70
	s_add_i32 s18, 16, 0x119f0
	v_mov_b32_e32 v64, s18
	v_mov_b32_e32 v65, s17
	v_cndmask_b32_e64 v64, v64, v65, s[20:21]
	s_addk_i32 s16, 0x78
	s_add_i32 s17, 16, 0x119f8
	ds_read2_b32 v[152:153], v64 offset1:1
	v_mov_b32_e32 v64, s17
	v_mov_b32_e32 v65, s16
	v_cndmask_b32_e64 v64, v64, v65, s[20:21]
	v_cndmask_b32_e64 v62, v62, v63, s[20:21]
	ds_read2_b32 v[158:159], v64 offset1:1
	v_mov_b32_e32 v64, v1
	ds_read2_b32 v[62:63], v62 offset1:1
	ds_read_b128 v[220:223], v1 offset:45168
	ds_read_b128 v[224:227], v1 offset:45072
	ds_read_b128 v[228:231], v1 offset:45088
	ds_read_b128 v[232:235], v1 offset:45104
	s_waitcnt lgkmcnt(4)
	s_waitcnt lgkmcnt(3)
	v_pk_mul_f32 v[64:65], v[60:61], v[222:223] op_sel_hi:[0,1]
	v_pk_fma_f32 v[64:65], v[150:151], v[62:63], v[64:65] neg_lo:[0,0,1] neg_hi:[0,0,1]
	s_waitcnt lgkmcnt(2)
	v_pk_mul_f32 v[150:151], v[60:61], v[226:227] op_sel_hi:[0,1]
	ds_read_b128 v[236:239], v1 offset:45120
	v_pk_fma_f32 v[62:63], v[60:61], v[224:225], v[60:61] op_sel_hi:[0,1,1] neg_lo:[1,0,0] neg_hi:[1,0,0]
	v_pk_fma_f32 v[154:155], v[120:121], v[66:67], v[150:151] neg_lo:[0,0,1] neg_hi:[0,0,1]
	s_waitcnt lgkmcnt(2)
	v_pk_mul_f32 v[66:67], v[60:61], v[228:229] op_sel_hi:[0,1]
	v_pk_fma_f32 v[150:151], v[124:125], v[122:123], v[66:67] neg_lo:[0,0,1] neg_hi:[0,0,1]
	ds_read_b128 v[224:227], v1 offset:45136
	v_pk_mul_f32 v[66:67], v[60:61], v[230:231] op_sel_hi:[0,1]
	v_pk_fma_f32 v[156:157], v[126:127], v[200:201], v[66:67] neg_lo:[0,0,1] neg_hi:[0,0,1]
	s_waitcnt lgkmcnt(2)
	v_pk_mul_f32 v[66:67], v[60:61], v[232:233] op_sel_hi:[0,1]
	v_pk_fma_f32 v[128:129], v[128:129], v[202:203], v[66:67] neg_lo:[0,0,1] neg_hi:[0,0,1]
	ds_read_b128 v[228:231], v1 offset:45152
	v_pk_mul_f32 v[66:67], v[60:61], v[234:235] op_sel_hi:[0,1]
	v_pk_fma_f32 v[130:131], v[130:131], v[204:205], v[66:67] neg_lo:[0,0,1] neg_hi:[0,0,1]
	s_waitcnt lgkmcnt(2)
	v_pk_mul_f32 v[66:67], v[60:61], v[236:237] op_sel_hi:[0,1]
	v_pk_fma_f32 v[132:133], v[132:133], v[206:207], v[66:67] neg_lo:[0,0,1] neg_hi:[0,0,1]
	v_pk_mul_f32 v[66:67], v[60:61], v[238:239] op_sel_hi:[0,1]
	ds_read_b128 v[232:235], v1 offset:45184
	v_pk_fma_f32 v[134:135], v[134:135], v[208:209], v[66:67] neg_lo:[0,0,1] neg_hi:[0,0,1]
	s_waitcnt lgkmcnt(2)
	v_pk_mul_f32 v[66:67], v[60:61], v[224:225] op_sel_hi:[0,1]
	v_pk_fma_f32 v[124:125], v[136:137], v[210:211], v[66:67] neg_lo:[0,0,1] neg_hi:[0,0,1]
	v_pk_mul_f32 v[66:67], v[60:61], v[226:227] op_sel_hi:[0,1]
	v_pk_fma_f32 v[126:127], v[138:139], v[212:213], v[66:67] neg_lo:[0,0,1] neg_hi:[0,0,1]
	ds_read_b128 v[224:227], v1 offset:45216
	s_waitcnt lgkmcnt(2)
	v_pk_mul_f32 v[66:67], v[60:61], v[228:229] op_sel_hi:[0,1]
	ds_read_b128 v[236:239], v1 offset:45232
	v_pk_fma_f32 v[120:121], v[140:141], v[214:215], v[66:67] neg_lo:[0,0,1] neg_hi:[0,0,1]
	ds_read_b128 v[240:243], v1 offset:45248
	v_pk_mul_f32 v[66:67], v[60:61], v[230:231] op_sel_hi:[0,1]
	v_pk_fma_f32 v[122:123], v[142:143], v[216:217], v[66:67] neg_lo:[0,0,1] neg_hi:[0,0,1]
	v_pk_mul_f32 v[66:67], v[60:61], v[220:221] op_sel_hi:[0,1]
	ds_read_b128 v[220:223], v1 offset:45264
	s_waitcnt lgkmcnt(4)
	v_pk_mul_f32 v[136:137], v[60:61], v[232:233] op_sel_hi:[0,1]
	v_pk_fma_f32 v[66:67], v[148:149], v[218:219], v[66:67] neg_lo:[0,0,1] neg_hi:[0,0,1]
	v_pk_fma_f32 v[148:149], v[144:145], v[152:153], v[136:137] neg_lo:[0,0,1] neg_hi:[0,0,1]
	ds_read_b128 v[228:231], v1 offset:45280
	v_pk_mul_f32 v[60:61], v[60:61], v[234:235] op_sel_hi:[0,1]
	v_pk_fma_f32 v[60:61], v[146:147], v[158:159], v[60:61] neg_lo:[0,0,1] neg_hi:[0,0,1]
	ds_read_b128 v[232:235], v1 offset:45296
	s_waitcnt lgkmcnt(5)
	v_pk_fma_f32 v[138:139], v[62:63], v[226:227], v[154:155] op_sel:[1,0,0] neg_lo:[1,0,0] neg_hi:[1,0,0]
	s_waitcnt lgkmcnt(4)
	v_pk_fma_f32 v[140:141], v[62:63], v[236:237], v[150:151] op_sel:[1,0,0] neg_lo:[1,0,0] neg_hi:[1,0,0]
	ds_read_b128 v[244:247], v1 offset:45312
	s_waitcnt lgkmcnt(4)
	v_pk_fma_f32 v[144:145], v[62:63], v[240:241], v[128:129] op_sel:[1,0,0] neg_lo:[1,0,0] neg_hi:[1,0,0]
	v_pk_fma_f32 v[146:147], v[62:63], v[242:243], v[130:131] op_sel:[1,0,0] neg_lo:[1,0,0] neg_hi:[1,0,0]
	ds_read_b128 v[240:243], v1 offset:45328
	v_pk_fma_f32 v[142:143], v[62:63], v[238:239], v[156:157] op_sel:[1,0,0] neg_lo:[1,0,0] neg_hi:[1,0,0]
	s_waitcnt lgkmcnt(4)
	v_pk_fma_f32 v[132:133], v[62:63], v[220:221], v[132:133] op_sel:[1,0,0] neg_lo:[1,0,0] neg_hi:[1,0,0]
	ds_read_b128 v[236:239], v1 offset:45360
	v_pk_fma_f32 v[134:135], v[62:63], v[222:223], v[134:135] op_sel:[1,0,0] neg_lo:[1,0,0] neg_hi:[1,0,0]
	v_pk_fma_f32 v[136:137], v[62:63], v[224:225], v[62:63] op_sel:[1,0,0] neg_lo:[1,0,0] neg_hi:[1,0,0]
	ds_read_b128 v[220:223], v1 offset:45376
	s_waitcnt lgkmcnt(5)
	v_pk_fma_f32 v[150:151], v[62:63], v[228:229], v[124:125] op_sel:[1,0,0] neg_lo:[1,0,0] neg_hi:[1,0,0]
	v_pk_fma_f32 v[152:153], v[62:63], v[230:231], v[126:127] op_sel:[1,0,0] neg_lo:[1,0,0] neg_hi:[1,0,0]
	ds_read_b128 v[224:227], v1 offset:45392
	s_waitcnt lgkmcnt(5)
	v_pk_fma_f32 v[154:155], v[62:63], v[232:233], v[120:121] op_sel:[1,0,0] neg_lo:[1,0,0] neg_hi:[1,0,0]
	v_pk_fma_f32 v[156:157], v[62:63], v[234:235], v[122:123] op_sel:[1,0,0] neg_lo:[1,0,0] neg_hi:[1,0,0]
	s_waitcnt lgkmcnt(4)
	v_pk_fma_f32 v[158:159], v[62:63], v[244:245], v[66:67] op_sel:[1,0,0] neg_lo:[1,0,0] neg_hi:[1,0,0]
	v_pk_fma_f32 v[182:183], v[62:63], v[246:247], v[64:65] op_sel:[1,0,0] neg_lo:[1,0,0] neg_hi:[1,0,0]
	ds_read_b128 v[228:231], v1 offset:45408
	ds_read_b128 v[232:235], v1 offset:45424
	s_waitcnt lgkmcnt(5)
	v_pk_fma_f32 v[184:185], v[62:63], v[242:243], v[60:61] op_sel:[1,0,0] neg_lo:[1,0,0] neg_hi:[1,0,0]
	v_pk_fma_f32 v[148:149], v[62:63], v[240:241], v[148:149] op_sel:[1,0,0] neg_lo:[1,0,0] neg_hi:[1,0,0]
	ds_read_b128 v[240:243], v1 offset:45440
	s_waitcnt lgkmcnt(5)
	v_pk_fma_f32 v[122:123], v[138:139], v[236:237], v[136:137] op_sel_hi:[0,1,1] neg_lo:[1,0,0] neg_hi:[1,0,0]
	v_pk_fma_f32 v[120:121], v[138:139], v[238:239], v[138:139] op_sel_hi:[0,1,1] neg_lo:[1,0,0] neg_hi:[1,0,0]
	ds_read_b128 v[236:239], v1 offset:45456
	s_waitcnt lgkmcnt(5)
	v_pk_fma_f32 v[136:137], v[138:139], v[220:221], v[140:141] op_sel_hi:[0,1,1] neg_lo:[1,0,0] neg_hi:[1,0,0]
	v_pk_fma_f32 v[140:141], v[138:139], v[222:223], v[142:143] op_sel_hi:[0,1,1] neg_lo:[1,0,0] neg_hi:[1,0,0]
	ds_read_b128 v[220:223], v1 offset:45472
	s_waitcnt lgkmcnt(5)
	v_pk_fma_f32 v[142:143], v[138:139], v[224:225], v[144:145] op_sel_hi:[0,1,1] neg_lo:[1,0,0] neg_hi:[1,0,0]
	v_pk_fma_f32 v[144:145], v[138:139], v[226:227], v[146:147] op_sel_hi:[0,1,1] neg_lo:[1,0,0] neg_hi:[1,0,0]
	ds_read_b128 v[224:227], v1 offset:45520
	s_waitcnt lgkmcnt(4)
	v_pk_fma_f32 v[146:147], v[138:139], v[232:233], v[150:151] op_sel_hi:[0,1,1] neg_lo:[1,0,0] neg_hi:[1,0,0]
	v_pk_fma_f32 v[150:151], v[138:139], v[234:235], v[152:153] op_sel_hi:[0,1,1] neg_lo:[1,0,0] neg_hi:[1,0,0]
	ds_read_b128 v[232:235], v1 offset:45536
	v_pk_fma_f32 v[132:133], v[138:139], v[228:229], v[132:133] op_sel_hi:[0,1,1] neg_lo:[1,0,0] neg_hi:[1,0,0]
	v_pk_fma_f32 v[134:135], v[138:139], v[230:231], v[134:135] op_sel_hi:[0,1,1] neg_lo:[1,0,0] neg_hi:[1,0,0]
	ds_read_b128 v[228:231], v1 offset:45552
	s_waitcnt lgkmcnt(5)
	v_pk_fma_f32 v[152:153], v[138:139], v[240:241], v[154:155] op_sel_hi:[0,1,1] neg_lo:[1,0,0] neg_hi:[1,0,0]
	v_pk_fma_f32 v[154:155], v[138:139], v[242:243], v[156:157] op_sel_hi:[0,1,1] neg_lo:[1,0,0] neg_hi:[1,0,0]
	s_waitcnt lgkmcnt(4)
	v_pk_fma_f32 v[156:157], v[138:139], v[236:237], v[158:159] op_sel_hi:[0,1,1] neg_lo:[1,0,0] neg_hi:[1,0,0]
	v_pk_fma_f32 v[158:159], v[138:139], v[238:239], v[182:183] op_sel_hi:[0,1,1] neg_lo:[1,0,0] neg_hi:[1,0,0]
	ds_read_b128 v[236:239], v1 offset:45568
	ds_read_b128 v[240:243], v1 offset:45584
	s_waitcnt lgkmcnt(5)
	v_pk_fma_f32 v[148:149], v[138:139], v[220:221], v[148:149] op_sel_hi:[0,1,1] neg_lo:[1,0,0] neg_hi:[1,0,0]
	v_pk_fma_f32 v[138:139], v[138:139], v[222:223], v[184:185] op_sel_hi:[0,1,1] neg_lo:[1,0,0] neg_hi:[1,0,0]
	ds_read_b128 v[220:223], v1 offset:45600
	s_waitcnt lgkmcnt(5)
	v_pk_fma_f32 v[136:137], v[120:121], v[224:225], v[136:137] op_sel:[1,0,0] neg_lo:[1,0,0] neg_hi:[1,0,0]
	v_pk_fma_f32 v[140:141], v[120:121], v[226:227], v[140:141] op_sel:[1,0,0] neg_lo:[1,0,0] neg_hi:[1,0,0]
	ds_read_b128 v[224:227], v1 offset:45616
	s_waitcnt lgkmcnt(5)
	v_pk_fma_f32 v[142:143], v[120:121], v[232:233], v[142:143] op_sel:[1,0,0] neg_lo:[1,0,0] neg_hi:[1,0,0]
	v_pk_fma_f32 v[144:145], v[120:121], v[234:235], v[144:145] op_sel:[1,0,0] neg_lo:[1,0,0] neg_hi:[1,0,0]
	ds_read_b128 v[232:235], v1 offset:45664
	s_waitcnt lgkmcnt(5)
	v_pk_fma_f32 v[132:133], v[120:121], v[228:229], v[132:133] op_sel:[1,0,0] neg_lo:[1,0,0] neg_hi:[1,0,0]
	v_pk_fma_f32 v[134:135], v[120:121], v[230:231], v[134:135] op_sel:[1,0,0] neg_lo:[1,0,0] neg_hi:[1,0,0]
	ds_read_b128 v[228:231], v1 offset:45680
	s_waitcnt lgkmcnt(4)
	v_pk_fma_f32 v[152:153], v[120:121], v[240:241], v[152:153] op_sel:[1,0,0] neg_lo:[1,0,0] neg_hi:[1,0,0]
	v_pk_fma_f32 v[154:155], v[120:121], v[242:243], v[154:155] op_sel:[1,0,0] neg_lo:[1,0,0] neg_hi:[1,0,0]
	ds_read_b128 v[240:243], v1 offset:45696
	v_pk_fma_f32 v[146:147], v[120:121], v[236:237], v[146:147] op_sel:[1,0,0] neg_lo:[1,0,0] neg_hi:[1,0,0]
	v_pk_fma_f32 v[150:151], v[120:121], v[238:239], v[150:151] op_sel:[1,0,0] neg_lo:[1,0,0] neg_hi:[1,0,0]
	s_waitcnt lgkmcnt(4)
	v_pk_fma_f32 v[156:157], v[120:121], v[220:221], v[156:157] op_sel:[1,0,0] neg_lo:[1,0,0] neg_hi:[1,0,0]
	v_pk_fma_f32 v[158:159], v[120:121], v[222:223], v[158:159] op_sel:[1,0,0] neg_lo:[1,0,0] neg_hi:[1,0,0]
	ds_read_b128 v[220:223], v1 offset:45712
	ds_read_b128 v[236:239], v1 offset:45728
	s_waitcnt lgkmcnt(5)
	v_pk_fma_f32 v[148:149], v[120:121], v[224:225], v[148:149] op_sel:[1,0,0] neg_lo:[1,0,0] neg_hi:[1,0,0]
	v_pk_fma_f32 v[138:139], v[120:121], v[226:227], v[138:139] op_sel:[1,0,0] neg_lo:[1,0,0] neg_hi:[1,0,0]
	ds_read_b128 v[224:227], v1 offset:45744
	s_waitcnt lgkmcnt(5)
	v_pk_fma_f32 v[182:183], v[136:137], v[232:233], v[136:137] op_sel_hi:[0,1,1] neg_lo:[1,0,0] neg_hi:[1,0,0]
	v_pk_fma_f32 v[140:141], v[136:137], v[234:235], v[140:141] op_sel_hi:[0,1,1] neg_lo:[1,0,0] neg_hi:[1,0,0]
	ds_read_b128 v[232:235], v1 offset:45760
	s_waitcnt lgkmcnt(5)
	v_pk_fma_f32 v[142:143], v[136:137], v[228:229], v[142:143] op_sel_hi:[0,1,1] neg_lo:[1,0,0] neg_hi:[1,0,0]
	v_pk_fma_f32 v[144:145], v[136:137], v[230:231], v[144:145] op_sel_hi:[0,1,1] neg_lo:[1,0,0] neg_hi:[1,0,0]
	ds_read_b128 v[228:231], v1 offset:45808
	s_waitcnt lgkmcnt(5)
	v_pk_fma_f32 v[132:133], v[136:137], v[240:241], v[132:133] op_sel_hi:[0,1,1] neg_lo:[1,0,0] neg_hi:[1,0,0]
	v_pk_fma_f32 v[134:135], v[136:137], v[242:243], v[134:135] op_sel_hi:[0,1,1] neg_lo:[1,0,0] neg_hi:[1,0,0]
	ds_read_b128 v[240:243], v1 offset:45824
	s_waitcnt lgkmcnt(4)
	v_pk_fma_f32 v[152:153], v[136:137], v[236:237], v[152:153] op_sel_hi:[0,1,1] neg_lo:[1,0,0] neg_hi:[1,0,0]
	v_pk_fma_f32 v[154:155], v[136:137], v[238:239], v[154:155] op_sel_hi:[0,1,1] neg_lo:[1,0,0] neg_hi:[1,0,0]
	ds_read_b128 v[236:239], v1 offset:45840
	v_pk_fma_f32 v[146:147], v[136:137], v[220:221], v[146:147] op_sel_hi:[0,1,1] neg_lo:[1,0,0] neg_hi:[1,0,0]
	v_pk_fma_f32 v[150:151], v[136:137], v[222:223], v[150:151] op_sel_hi:[0,1,1] neg_lo:[1,0,0] neg_hi:[1,0,0]
	s_waitcnt lgkmcnt(4)
	v_pk_fma_f32 v[156:157], v[136:137], v[224:225], v[156:157] op_sel_hi:[0,1,1] neg_lo:[1,0,0] neg_hi:[1,0,0]
	v_pk_fma_f32 v[158:159], v[136:137], v[226:227], v[158:159] op_sel_hi:[0,1,1] neg_lo:[1,0,0] neg_hi:[1,0,0]
	ds_read_b128 v[220:223], v1 offset:45856
	ds_read_b128 v[224:227], v1 offset:45872
	s_waitcnt lgkmcnt(5)
	v_pk_fma_f32 v[148:149], v[136:137], v[232:233], v[148:149] op_sel_hi:[0,1,1] neg_lo:[1,0,0] neg_hi:[1,0,0]
	v_pk_fma_f32 v[136:137], v[136:137], v[234:235], v[138:139] op_sel_hi:[0,1,1] neg_lo:[1,0,0] neg_hi:[1,0,0]
	ds_read_b128 v[232:235], v1 offset:45888
	s_waitcnt lgkmcnt(5)
	v_pk_fma_f32 v[138:139], v[182:183], v[228:229], v[182:183] op_sel:[1,0,0] neg_lo:[1,0,0] neg_hi:[1,0,0]
	v_pk_fma_f32 v[140:141], v[182:183], v[230:231], v[140:141] op_sel:[1,0,0] neg_lo:[1,0,0] neg_hi:[1,0,0]
	ds_read_b128 v[228:231], v1 offset:45904
	s_waitcnt lgkmcnt(5)
	v_pk_fma_f32 v[142:143], v[182:183], v[240:241], v[142:143] op_sel:[1,0,0] neg_lo:[1,0,0] neg_hi:[1,0,0]
	v_pk_fma_f32 v[144:145], v[182:183], v[242:243], v[144:145] op_sel:[1,0,0] neg_lo:[1,0,0] neg_hi:[1,0,0]
	ds_read_b128 v[240:243], v1 offset:45952
	s_waitcnt lgkmcnt(5)
	v_pk_fma_f32 v[184:185], v[182:183], v[236:237], v[132:133] op_sel:[1,0,0] neg_lo:[1,0,0] neg_hi:[1,0,0]
	v_pk_fma_f32 v[186:187], v[182:183], v[238:239], v[134:135] op_sel:[1,0,0] neg_lo:[1,0,0] neg_hi:[1,0,0]
	ds_read_b128 v[236:239], v1 offset:45968
	s_waitcnt lgkmcnt(4)
	v_pk_fma_f32 v[152:153], v[182:183], v[224:225], v[152:153] op_sel:[1,0,0] neg_lo:[1,0,0] neg_hi:[1,0,0]
	v_pk_fma_f32 v[154:155], v[182:183], v[226:227], v[154:155] op_sel:[1,0,0] neg_lo:[1,0,0] neg_hi:[1,0,0]
	ds_read_b128 v[224:227], v1 offset:45984
	v_pk_fma_f32 v[146:147], v[182:183], v[220:221], v[146:147] op_sel:[1,0,0] neg_lo:[1,0,0] neg_hi:[1,0,0]
	v_pk_fma_f32 v[150:151], v[182:183], v[222:223], v[150:151] op_sel:[1,0,0] neg_lo:[1,0,0] neg_hi:[1,0,0]
	s_waitcnt lgkmcnt(4)
	v_pk_fma_f32 v[156:157], v[182:183], v[232:233], v[156:157] op_sel:[1,0,0] neg_lo:[1,0,0] neg_hi:[1,0,0]
	v_pk_fma_f32 v[158:159], v[182:183], v[234:235], v[158:159] op_sel:[1,0,0] neg_lo:[1,0,0] neg_hi:[1,0,0]
	ds_read_b128 v[220:223], v1 offset:46000
	ds_read_b128 v[232:235], v1 offset:46016
	s_waitcnt lgkmcnt(5)
	v_pk_fma_f32 v[148:149], v[182:183], v[228:229], v[148:149] op_sel:[1,0,0] neg_lo:[1,0,0] neg_hi:[1,0,0]
	v_pk_fma_f32 v[136:137], v[182:183], v[230:231], v[136:137] op_sel:[1,0,0] neg_lo:[1,0,0] neg_hi:[1,0,0]
	ds_read_b128 v[228:231], v1 offset:46032
	s_waitcnt lgkmcnt(5)
	v_pk_fma_f32 v[124:125], v[140:141], v[240:241], v[138:139] op_sel_hi:[0,1,1] neg_lo:[1,0,0] neg_hi:[1,0,0]
	v_pk_fma_f32 v[126:127], v[140:141], v[242:243], v[140:141] op_sel_hi:[0,1,1] neg_lo:[1,0,0] neg_hi:[1,0,0]
	ds_read_b128 v[240:243], v1 offset:46048
	s_waitcnt lgkmcnt(5)
	v_pk_fma_f32 v[138:139], v[140:141], v[236:237], v[142:143] op_sel_hi:[0,1,1] neg_lo:[1,0,0] neg_hi:[1,0,0]
	v_pk_fma_f32 v[142:143], v[140:141], v[238:239], v[144:145] op_sel_hi:[0,1,1] neg_lo:[1,0,0] neg_hi:[1,0,0]
	ds_read_b128 v[236:239], v1 offset:46112
	s_waitcnt lgkmcnt(5)
	v_pk_fma_f32 v[144:145], v[140:141], v[224:225], v[184:185] op_sel_hi:[0,1,1] neg_lo:[1,0,0] neg_hi:[1,0,0]
	v_pk_fma_f32 v[182:183], v[140:141], v[226:227], v[186:187] op_sel_hi:[0,1,1] neg_lo:[1,0,0] neg_hi:[1,0,0]
	ds_read_b128 v[224:227], v1 offset:46128
	s_waitcnt lgkmcnt(4)
	v_pk_fma_f32 v[152:153], v[140:141], v[232:233], v[152:153] op_sel_hi:[0,1,1] neg_lo:[1,0,0] neg_hi:[1,0,0]
	v_pk_fma_f32 v[154:155], v[140:141], v[234:235], v[154:155] op_sel_hi:[0,1,1] neg_lo:[1,0,0] neg_hi:[1,0,0]
	ds_read_b128 v[232:235], v1 offset:46144
	v_pk_fma_f32 v[146:147], v[140:141], v[220:221], v[146:147] op_sel_hi:[0,1,1] neg_lo:[1,0,0] neg_hi:[1,0,0]
	v_pk_fma_f32 v[150:151], v[140:141], v[222:223], v[150:151] op_sel_hi:[0,1,1] neg_lo:[1,0,0] neg_hi:[1,0,0]
	s_waitcnt lgkmcnt(4)
	v_pk_fma_f32 v[156:157], v[140:141], v[228:229], v[156:157] op_sel_hi:[0,1,1] neg_lo:[1,0,0] neg_hi:[1,0,0]
	v_pk_fma_f32 v[158:159], v[140:141], v[230:231], v[158:159] op_sel_hi:[0,1,1] neg_lo:[1,0,0] neg_hi:[1,0,0]
	ds_read_b128 v[220:223], v1 offset:46160
	ds_read_b128 v[228:231], v1 offset:46176
	s_waitcnt lgkmcnt(5)
	v_pk_fma_f32 v[148:149], v[140:141], v[240:241], v[148:149] op_sel_hi:[0,1,1] neg_lo:[1,0,0] neg_hi:[1,0,0]
	v_pk_fma_f32 v[136:137], v[140:141], v[242:243], v[136:137] op_sel_hi:[0,1,1] neg_lo:[1,0,0] neg_hi:[1,0,0]
	ds_read_b128 v[240:243], v1 offset:46192
	s_waitcnt lgkmcnt(5)
	v_pk_fma_f32 v[138:139], v[126:127], v[236:237], v[138:139] op_sel:[1,0,0] neg_lo:[1,0,0] neg_hi:[1,0,0]
	v_pk_fma_f32 v[140:141], v[126:127], v[238:239], v[142:143] op_sel:[1,0,0] neg_lo:[1,0,0] neg_hi:[1,0,0]
	ds_read_b128 v[236:239], v1 offset:46256
	s_waitcnt lgkmcnt(5)
	v_pk_fma_f32 v[142:143], v[126:127], v[224:225], v[144:145] op_sel:[1,0,0] neg_lo:[1,0,0] neg_hi:[1,0,0]
	v_pk_fma_f32 v[144:145], v[126:127], v[226:227], v[182:183] op_sel:[1,0,0] neg_lo:[1,0,0] neg_hi:[1,0,0]
	ds_read_b128 v[224:227], v1 offset:46272
	s_waitcnt lgkmcnt(5)
	v_pk_fma_f32 v[146:147], v[126:127], v[232:233], v[146:147] op_sel:[1,0,0] neg_lo:[1,0,0] neg_hi:[1,0,0]
	v_pk_fma_f32 v[150:151], v[126:127], v[234:235], v[150:151] op_sel:[1,0,0] neg_lo:[1,0,0] neg_hi:[1,0,0]
	ds_read_b128 v[232:235], v1 offset:46288
	s_waitcnt lgkmcnt(4)
	v_pk_fma_f32 v[156:157], v[126:127], v[228:229], v[156:157] op_sel:[1,0,0] neg_lo:[1,0,0] neg_hi:[1,0,0]
	v_pk_fma_f32 v[158:159], v[126:127], v[230:231], v[158:159] op_sel:[1,0,0] neg_lo:[1,0,0] neg_hi:[1,0,0]
	v_pk_fma_f32 v[152:153], v[126:127], v[220:221], v[152:153] op_sel:[1,0,0] neg_lo:[1,0,0] neg_hi:[1,0,0]
	v_pk_fma_f32 v[154:155], v[126:127], v[222:223], v[154:155] op_sel:[1,0,0] neg_lo:[1,0,0] neg_hi:[1,0,0]
	ds_read_b128 v[220:223], v1 offset:46304
	ds_read_b128 v[228:231], v1 offset:46320
	s_waitcnt lgkmcnt(5)
	v_pk_fma_f32 v[148:149], v[126:127], v[240:241], v[148:149] op_sel:[1,0,0] neg_lo:[1,0,0] neg_hi:[1,0,0]
	v_pk_fma_f32 v[136:137], v[126:127], v[242:243], v[136:137] op_sel:[1,0,0] neg_lo:[1,0,0] neg_hi:[1,0,0]
	ds_read_b128 v[240:243], v1 offset:46336
	s_waitcnt lgkmcnt(5)
	v_pk_fma_f32 v[182:183], v[138:139], v[236:237], v[138:139] op_sel_hi:[0,1,1] neg_lo:[1,0,0] neg_hi:[1,0,0]
	v_pk_fma_f32 v[140:141], v[138:139], v[238:239], v[140:141] op_sel_hi:[0,1,1] neg_lo:[1,0,0] neg_hi:[1,0,0]
	ds_read_b128 v[236:239], v1 offset:46400
	s_waitcnt lgkmcnt(5)
	v_pk_fma_f32 v[142:143], v[138:139], v[224:225], v[142:143] op_sel_hi:[0,1,1] neg_lo:[1,0,0] neg_hi:[1,0,0]
	v_pk_fma_f32 v[144:145], v[138:139], v[226:227], v[144:145] op_sel_hi:[0,1,1] neg_lo:[1,0,0] neg_hi:[1,0,0]
	ds_read_b128 v[224:227], v1 offset:46416
	s_waitcnt lgkmcnt(5)
	v_pk_fma_f32 v[146:147], v[138:139], v[232:233], v[146:147] op_sel_hi:[0,1,1] neg_lo:[1,0,0] neg_hi:[1,0,0]
	v_pk_fma_f32 v[150:151], v[138:139], v[234:235], v[150:151] op_sel_hi:[0,1,1] neg_lo:[1,0,0] neg_hi:[1,0,0]
	ds_read_b128 v[232:235], v1 offset:46432
	s_waitcnt lgkmcnt(4)
	v_pk_fma_f32 v[156:157], v[138:139], v[228:229], v[156:157] op_sel_hi:[0,1,1] neg_lo:[1,0,0] neg_hi:[1,0,0]
	v_pk_fma_f32 v[158:159], v[138:139], v[230:231], v[158:159] op_sel_hi:[0,1,1] neg_lo:[1,0,0] neg_hi:[1,0,0]
	v_pk_fma_f32 v[152:153], v[138:139], v[220:221], v[152:153] op_sel_hi:[0,1,1] neg_lo:[1,0,0] neg_hi:[1,0,0]
	v_pk_fma_f32 v[154:155], v[138:139], v[222:223], v[154:155] op_sel_hi:[0,1,1] neg_lo:[1,0,0] neg_hi:[1,0,0]
	ds_read_b128 v[220:223], v1 offset:46448
	ds_read_b128 v[228:231], v1 offset:46464
	s_waitcnt lgkmcnt(5)
	v_pk_fma_f32 v[148:149], v[138:139], v[240:241], v[148:149] op_sel_hi:[0,1,1] neg_lo:[1,0,0] neg_hi:[1,0,0]
	v_pk_fma_f32 v[136:137], v[138:139], v[242:243], v[136:137] op_sel_hi:[0,1,1] neg_lo:[1,0,0] neg_hi:[1,0,0]
	ds_read_b128 v[240:243], v1 offset:46480
	s_waitcnt lgkmcnt(5)
	v_pk_fma_f32 v[184:185], v[182:183], v[236:237], v[182:183] op_sel:[1,0,0] neg_lo:[1,0,0] neg_hi:[1,0,0]
	v_pk_fma_f32 v[140:141], v[182:183], v[238:239], v[140:141] op_sel:[1,0,0] neg_lo:[1,0,0] neg_hi:[1,0,0]
	ds_read_b128 v[236:239], v1 offset:46544
	s_waitcnt lgkmcnt(5)
	v_pk_fma_f32 v[142:143], v[182:183], v[224:225], v[142:143] op_sel:[1,0,0] neg_lo:[1,0,0] neg_hi:[1,0,0]
	v_pk_fma_f32 v[144:145], v[182:183], v[226:227], v[144:145] op_sel:[1,0,0] neg_lo:[1,0,0] neg_hi:[1,0,0]
	ds_read_b128 v[224:227], v1 offset:46560
	s_waitcnt lgkmcnt(5)
	v_pk_fma_f32 v[146:147], v[182:183], v[232:233], v[146:147] op_sel:[1,0,0] neg_lo:[1,0,0] neg_hi:[1,0,0]
	v_pk_fma_f32 v[150:151], v[182:183], v[234:235], v[150:151] op_sel:[1,0,0] neg_lo:[1,0,0] neg_hi:[1,0,0]
	ds_read_b128 v[232:235], v1 offset:46576
	s_waitcnt lgkmcnt(4)
	v_pk_fma_f32 v[156:157], v[182:183], v[228:229], v[156:157] op_sel:[1,0,0] neg_lo:[1,0,0] neg_hi:[1,0,0]
	v_pk_fma_f32 v[158:159], v[182:183], v[230:231], v[158:159] op_sel:[1,0,0] neg_lo:[1,0,0] neg_hi:[1,0,0]
	v_pk_fma_f32 v[152:153], v[182:183], v[220:221], v[152:153] op_sel:[1,0,0] neg_lo:[1,0,0] neg_hi:[1,0,0]
	v_pk_fma_f32 v[154:155], v[182:183], v[222:223], v[154:155] op_sel:[1,0,0] neg_lo:[1,0,0] neg_hi:[1,0,0]
	ds_read_b128 v[220:223], v1 offset:46592
	ds_read_b128 v[228:231], v1 offset:46608
	s_waitcnt lgkmcnt(5)
	v_pk_fma_f32 v[148:149], v[182:183], v[240:241], v[148:149] op_sel:[1,0,0] neg_lo:[1,0,0] neg_hi:[1,0,0]
	v_pk_fma_f32 v[182:183], v[182:183], v[242:243], v[136:137] op_sel:[1,0,0] neg_lo:[1,0,0] neg_hi:[1,0,0]
	ds_read_b128 v[240:243], v1 offset:46624
	s_waitcnt lgkmcnt(5)
	v_pk_fma_f32 v[128:129], v[140:141], v[236:237], v[184:185] op_sel_hi:[0,1,1] neg_lo:[1,0,0] neg_hi:[1,0,0]
	v_pk_fma_f32 v[130:131], v[140:141], v[238:239], v[140:141] op_sel_hi:[0,1,1] neg_lo:[1,0,0] neg_hi:[1,0,0]
	ds_read_b128 v[236:239], v1 offset:46704
	s_waitcnt lgkmcnt(5)
	v_pk_fma_f32 v[142:143], v[140:141], v[224:225], v[142:143] op_sel_hi:[0,1,1] neg_lo:[1,0,0] neg_hi:[1,0,0]
	v_pk_fma_f32 v[144:145], v[140:141], v[226:227], v[144:145] op_sel_hi:[0,1,1] neg_lo:[1,0,0] neg_hi:[1,0,0]
	ds_read_b128 v[224:227], v1 offset:46720
	s_waitcnt lgkmcnt(5)
	v_pk_fma_f32 v[146:147], v[140:141], v[232:233], v[146:147] op_sel_hi:[0,1,1] neg_lo:[1,0,0] neg_hi:[1,0,0]
	v_pk_fma_f32 v[150:151], v[140:141], v[234:235], v[150:151] op_sel_hi:[0,1,1] neg_lo:[1,0,0] neg_hi:[1,0,0]
	ds_read_b128 v[232:235], v1 offset:46736
	s_waitcnt lgkmcnt(4)
	v_pk_fma_f32 v[156:157], v[140:141], v[228:229], v[156:157] op_sel_hi:[0,1,1] neg_lo:[1,0,0] neg_hi:[1,0,0]
	v_pk_fma_f32 v[158:159], v[140:141], v[230:231], v[158:159] op_sel_hi:[0,1,1] neg_lo:[1,0,0] neg_hi:[1,0,0]
	v_pk_fma_f32 v[152:153], v[140:141], v[220:221], v[152:153] op_sel_hi:[0,1,1] neg_lo:[1,0,0] neg_hi:[1,0,0]
	ds_read_b128 v[228:231], v1 offset:46752
	ds_read_b128 v[244:247], v1 offset:46768
	v_pk_fma_f32 v[154:155], v[140:141], v[222:223], v[154:155] op_sel_hi:[0,1,1] neg_lo:[1,0,0] neg_hi:[1,0,0]
	s_waitcnt lgkmcnt(5)
	v_pk_fma_f32 v[148:149], v[140:141], v[240:241], v[148:149] op_sel_hi:[0,1,1] neg_lo:[1,0,0] neg_hi:[1,0,0]
	v_pk_fma_f32 v[140:141], v[140:141], v[242:243], v[182:183] op_sel_hi:[0,1,1] neg_lo:[1,0,0] neg_hi:[1,0,0]
	ds_read_b128 v[220:223], v1 offset:46848
	s_waitcnt lgkmcnt(5)
	v_pk_fma_f32 v[142:143], v[130:131], v[236:237], v[142:143] op_sel:[1,0,0] neg_lo:[1,0,0] neg_hi:[1,0,0]
	v_pk_fma_f32 v[144:145], v[130:131], v[238:239], v[144:145] op_sel:[1,0,0] neg_lo:[1,0,0] neg_hi:[1,0,0]
	ds_read_b128 v[236:239], v1 offset:46864
	s_waitcnt lgkmcnt(5)
	v_pk_fma_f32 v[146:147], v[130:131], v[224:225], v[146:147] op_sel:[1,0,0] neg_lo:[1,0,0] neg_hi:[1,0,0]
	v_pk_fma_f32 v[150:151], v[130:131], v[226:227], v[150:151] op_sel:[1,0,0] neg_lo:[1,0,0] neg_hi:[1,0,0]
	ds_read_b128 v[224:227], v1 offset:46880
	s_waitcnt lgkmcnt(5)
	v_pk_fma_f32 v[152:153], v[130:131], v[232:233], v[152:153] op_sel:[1,0,0] neg_lo:[1,0,0] neg_hi:[1,0,0]
	v_pk_fma_f32 v[154:155], v[130:131], v[234:235], v[154:155] op_sel:[1,0,0] neg_lo:[1,0,0] neg_hi:[1,0,0]
	s_waitcnt lgkmcnt(3)
	v_pk_fma_f32 v[148:149], v[130:131], v[244:245], v[148:149] op_sel:[1,0,0] neg_lo:[1,0,0] neg_hi:[1,0,0]
	ds_read_b128 v[232:235], v1 offset:46896
	ds_read_b128 v[240:243], v1 offset:46912
	v_pk_fma_f32 v[156:157], v[130:131], v[228:229], v[156:157] op_sel:[1,0,0] neg_lo:[1,0,0] neg_hi:[1,0,0]
	v_pk_fma_f32 v[158:159], v[130:131], v[230:231], v[158:159] op_sel:[1,0,0] neg_lo:[1,0,0] neg_hi:[1,0,0]
	v_pk_fma_f32 v[140:141], v[130:131], v[246:247], v[140:141] op_sel:[1,0,0] neg_lo:[1,0,0] neg_hi:[1,0,0]
	ds_read_b128 v[228:231], v1 offset:46992
	s_waitcnt lgkmcnt(5)
	v_pk_fma_f32 v[182:183], v[142:143], v[220:221], v[142:143] op_sel_hi:[0,1,1] neg_lo:[1,0,0] neg_hi:[1,0,0]
	v_pk_fma_f32 v[144:145], v[142:143], v[222:223], v[144:145] op_sel_hi:[0,1,1] neg_lo:[1,0,0] neg_hi:[1,0,0]
	ds_read_b128 v[220:223], v1 offset:47008
	s_waitcnt lgkmcnt(5)
	v_pk_fma_f32 v[146:147], v[142:143], v[236:237], v[146:147] op_sel_hi:[0,1,1] neg_lo:[1,0,0] neg_hi:[1,0,0]
	v_pk_fma_f32 v[150:151], v[142:143], v[238:239], v[150:151] op_sel_hi:[0,1,1] neg_lo:[1,0,0] neg_hi:[1,0,0]
	ds_read_b128 v[236:239], v1 offset:47024
	s_waitcnt lgkmcnt(5)
	v_pk_fma_f32 v[152:153], v[142:143], v[224:225], v[152:153] op_sel_hi:[0,1,1] neg_lo:[1,0,0] neg_hi:[1,0,0]
	v_pk_fma_f32 v[154:155], v[142:143], v[226:227], v[154:155] op_sel_hi:[0,1,1] neg_lo:[1,0,0] neg_hi:[1,0,0]
	s_waitcnt lgkmcnt(3)
	v_pk_fma_f32 v[148:149], v[142:143], v[240:241], v[148:149] op_sel_hi:[0,1,1] neg_lo:[1,0,0] neg_hi:[1,0,0]
	ds_read_b128 v[224:227], v1 offset:47040
	ds_read_b128 v[244:247], v1 offset:47056
	v_pk_fma_f32 v[156:157], v[142:143], v[232:233], v[156:157] op_sel_hi:[0,1,1] neg_lo:[1,0,0] neg_hi:[1,0,0]
	v_pk_fma_f32 v[158:159], v[142:143], v[234:235], v[158:159] op_sel_hi:[0,1,1] neg_lo:[1,0,0] neg_hi:[1,0,0]
	v_pk_fma_f32 v[140:141], v[142:143], v[242:243], v[140:141] op_sel_hi:[0,1,1] neg_lo:[1,0,0] neg_hi:[1,0,0]
	ds_read_b128 v[232:235], v1 offset:47136
	s_waitcnt lgkmcnt(5)
	v_pk_fma_f32 v[184:185], v[182:183], v[228:229], v[182:183] op_sel:[1,0,0] neg_lo:[1,0,0] neg_hi:[1,0,0]
	v_pk_fma_f32 v[144:145], v[182:183], v[230:231], v[144:145] op_sel:[1,0,0] neg_lo:[1,0,0] neg_hi:[1,0,0]
	s_waitcnt lgkmcnt(4)
	v_pk_fma_f32 v[146:147], v[182:183], v[220:221], v[146:147] op_sel:[1,0,0] neg_lo:[1,0,0] neg_hi:[1,0,0]
	ds_read_b128 v[228:231], v1 offset:47152
	v_pk_fma_f32 v[150:151], v[182:183], v[222:223], v[150:151] op_sel:[1,0,0] neg_lo:[1,0,0] neg_hi:[1,0,0]
	s_waitcnt lgkmcnt(4)
	v_pk_fma_f32 v[152:153], v[182:183], v[236:237], v[152:153] op_sel:[1,0,0] neg_lo:[1,0,0] neg_hi:[1,0,0]
	ds_read_b128 v[220:223], v1 offset:47168
	ds_read_b128 v[240:243], v1 offset:47184
	v_pk_fma_f32 v[154:155], v[182:183], v[238:239], v[154:155] op_sel:[1,0,0] neg_lo:[1,0,0] neg_hi:[1,0,0]
	s_waitcnt lgkmcnt(4)
	v_pk_fma_f32 v[148:149], v[182:183], v[244:245], v[148:149] op_sel:[1,0,0] neg_lo:[1,0,0] neg_hi:[1,0,0]
	ds_read_b128 v[236:239], v1 offset:47200
	v_pk_fma_f32 v[156:157], v[182:183], v[224:225], v[156:157] op_sel:[1,0,0] neg_lo:[1,0,0] neg_hi:[1,0,0]
	v_pk_fma_f32 v[158:159], v[182:183], v[226:227], v[158:159] op_sel:[1,0,0] neg_lo:[1,0,0] neg_hi:[1,0,0]
	v_pk_fma_f32 v[182:183], v[182:183], v[246:247], v[140:141] op_sel:[1,0,0] neg_lo:[1,0,0] neg_hi:[1,0,0]
	ds_read_b128 v[224:227], v1 offset:47296
	s_waitcnt lgkmcnt(5)
	v_pk_fma_f32 v[132:133], v[144:145], v[232:233], v[184:185] op_sel_hi:[0,1,1] neg_lo:[1,0,0] neg_hi:[1,0,0]
	v_pk_fma_f32 v[134:135], v[144:145], v[234:235], v[144:145] op_sel_hi:[0,1,1] neg_lo:[1,0,0] neg_hi:[1,0,0]
	s_waitcnt lgkmcnt(2)
	v_pk_fma_f32 v[156:157], v[144:145], v[240:241], v[156:157] op_sel_hi:[0,1,1] neg_lo:[1,0,0] neg_hi:[1,0,0]
	ds_read_b128 v[232:235], v1 offset:47312
	v_pk_fma_f32 v[146:147], v[144:145], v[228:229], v[146:147] op_sel_hi:[0,1,1] neg_lo:[1,0,0] neg_hi:[1,0,0]
	v_pk_fma_f32 v[150:151], v[144:145], v[230:231], v[150:151] op_sel_hi:[0,1,1] neg_lo:[1,0,0] neg_hi:[1,0,0]
	ds_read_b128 v[228:231], v1 offset:47328
	ds_read_b128 v[244:247], v1 offset:47344
	v_pk_fma_f32 v[152:153], v[144:145], v[220:221], v[152:153] op_sel_hi:[0,1,1] neg_lo:[1,0,0] neg_hi:[1,0,0]
	s_waitcnt lgkmcnt(4)
	v_pk_fma_f32 v[148:149], v[144:145], v[236:237], v[148:149] op_sel_hi:[0,1,1] neg_lo:[1,0,0] neg_hi:[1,0,0]
	v_pk_fma_f32 v[154:155], v[144:145], v[222:223], v[154:155] op_sel_hi:[0,1,1] neg_lo:[1,0,0] neg_hi:[1,0,0]
	ds_read_b128 v[220:223], v1 offset:47440
	v_pk_fma_f32 v[158:159], v[144:145], v[242:243], v[158:159] op_sel_hi:[0,1,1] neg_lo:[1,0,0] neg_hi:[1,0,0]
	v_pk_fma_f32 v[144:145], v[144:145], v[238:239], v[182:183] op_sel_hi:[0,1,1] neg_lo:[1,0,0] neg_hi:[1,0,0]
	s_waitcnt lgkmcnt(4)
	v_pk_fma_f32 v[146:147], v[134:135], v[224:225], v[146:147] op_sel:[1,0,0] neg_lo:[1,0,0] neg_hi:[1,0,0]
	ds_read_b128 v[236:239], v1 offset:47456
	s_waitcnt lgkmcnt(2)
	v_pk_fma_f32 v[148:149], v[134:135], v[244:245], v[148:149] op_sel:[1,0,0] neg_lo:[1,0,0] neg_hi:[1,0,0]
	v_pk_fma_f32 v[150:151], v[134:135], v[226:227], v[150:151] op_sel:[1,0,0] neg_lo:[1,0,0] neg_hi:[1,0,0]
	ds_read_b128 v[224:227], v1 offset:47472
	ds_read_b128 v[240:243], v1 offset:47488
	v_pk_fma_f32 v[152:153], v[134:135], v[232:233], v[152:153] op_sel:[1,0,0] neg_lo:[1,0,0] neg_hi:[1,0,0]
	v_pk_fma_f32 v[154:155], v[134:135], v[234:235], v[154:155] op_sel:[1,0,0] neg_lo:[1,0,0] neg_hi:[1,0,0]
	v_pk_fma_f32 v[156:157], v[134:135], v[228:229], v[156:157] op_sel:[1,0,0] neg_lo:[1,0,0] neg_hi:[1,0,0]
	ds_read_b128 v[232:235], v1 offset:47584
	v_pk_fma_f32 v[158:159], v[134:135], v[230:231], v[158:159] op_sel:[1,0,0] neg_lo:[1,0,0] neg_hi:[1,0,0]
	v_pk_fma_f32 v[144:145], v[134:135], v[246:247], v[144:145] op_sel:[1,0,0] neg_lo:[1,0,0] neg_hi:[1,0,0]
	s_waitcnt lgkmcnt(4)
	v_pk_fma_f32 v[182:183], v[146:147], v[220:221], v[146:147] op_sel_hi:[0,1,1] neg_lo:[1,0,0] neg_hi:[1,0,0]
	ds_read_b128 v[228:231], v1 offset:47600
	ds_read_b128 v[244:247], v1 offset:47616
	s_waitcnt lgkmcnt(3)
	v_pk_fma_f32 v[148:149], v[146:147], v[240:241], v[148:149] op_sel_hi:[0,1,1] neg_lo:[1,0,0] neg_hi:[1,0,0]
	v_pk_fma_f32 v[150:151], v[146:147], v[222:223], v[150:151] op_sel_hi:[0,1,1] neg_lo:[1,0,0] neg_hi:[1,0,0]
	v_pk_fma_f32 v[152:153], v[146:147], v[236:237], v[152:153] op_sel_hi:[0,1,1] neg_lo:[1,0,0] neg_hi:[1,0,0]
	ds_read_b128 v[220:223], v1 offset:47632
	v_pk_fma_f32 v[154:155], v[146:147], v[238:239], v[154:155] op_sel_hi:[0,1,1] neg_lo:[1,0,0] neg_hi:[1,0,0]
	v_pk_fma_f32 v[156:157], v[146:147], v[224:225], v[156:157] op_sel_hi:[0,1,1] neg_lo:[1,0,0] neg_hi:[1,0,0]
	ds_read_b128 v[236:239], v1 offset:47728
	v_pk_fma_f32 v[158:159], v[146:147], v[226:227], v[158:159] op_sel_hi:[0,1,1] neg_lo:[1,0,0] neg_hi:[1,0,0]
	v_pk_fma_f32 v[144:145], v[146:147], v[242:243], v[144:145] op_sel_hi:[0,1,1] neg_lo:[1,0,0] neg_hi:[1,0,0]
	s_waitcnt lgkmcnt(4)
	v_pk_fma_f32 v[184:185], v[182:183], v[232:233], v[182:183] op_sel:[1,0,0] neg_lo:[1,0,0] neg_hi:[1,0,0]
	ds_read_b128 v[224:227], v1 offset:47744
	ds_read_b128 v[240:243], v1 offset:47760
	v_pk_fma_f32 v[150:151], v[182:183], v[234:235], v[150:151] op_sel:[1,0,0] neg_lo:[1,0,0] neg_hi:[1,0,0]
	s_waitcnt lgkmcnt(4)
	v_pk_fma_f32 v[156:157], v[182:183], v[244:245], v[156:157] op_sel:[1,0,0] neg_lo:[1,0,0] neg_hi:[1,0,0]
	v_pk_fma_f32 v[152:153], v[182:183], v[228:229], v[152:153] op_sel:[1,0,0] neg_lo:[1,0,0] neg_hi:[1,0,0]
	ds_read_b128 v[232:235], v1 offset:47776
	v_pk_fma_f32 v[154:155], v[182:183], v[230:231], v[154:155] op_sel:[1,0,0] neg_lo:[1,0,0] neg_hi:[1,0,0]
	v_pk_fma_f32 v[158:159], v[182:183], v[246:247], v[158:159] op_sel:[1,0,0] neg_lo:[1,0,0] neg_hi:[1,0,0]
	ds_read_b128 v[228:231], v1 offset:47888
	s_waitcnt lgkmcnt(5)
	v_pk_fma_f32 v[148:149], v[182:183], v[220:221], v[148:149] op_sel:[1,0,0] neg_lo:[1,0,0] neg_hi:[1,0,0]
	v_pk_fma_f32 v[182:183], v[182:183], v[222:223], v[144:145] op_sel:[1,0,0] neg_lo:[1,0,0] neg_hi:[1,0,0]
	s_waitcnt lgkmcnt(4)
	v_pk_fma_f32 v[136:137], v[150:151], v[236:237], v[184:185] op_sel_hi:[0,1,1] neg_lo:[1,0,0] neg_hi:[1,0,0]
	ds_read_b128 v[220:223], v1 offset:47904
	ds_read_b128 v[244:247], v1 offset:47920
	v_pk_fma_f32 v[138:139], v[150:151], v[238:239], v[150:151] op_sel_hi:[0,1,1] neg_lo:[1,0,0] neg_hi:[1,0,0]
	s_waitcnt lgkmcnt(4)
	v_pk_fma_f32 v[156:157], v[150:151], v[240:241], v[156:157] op_sel_hi:[0,1,1] neg_lo:[1,0,0] neg_hi:[1,0,0]
	v_pk_fma_f32 v[152:153], v[150:151], v[224:225], v[152:153] op_sel_hi:[0,1,1] neg_lo:[1,0,0] neg_hi:[1,0,0]
	ds_read_b128 v[236:239], v1 offset:48032
	v_pk_fma_f32 v[154:155], v[150:151], v[226:227], v[154:155] op_sel_hi:[0,1,1] neg_lo:[1,0,0] neg_hi:[1,0,0]
	v_pk_fma_f32 v[158:159], v[150:151], v[242:243], v[158:159] op_sel_hi:[0,1,1] neg_lo:[1,0,0] neg_hi:[1,0,0]
	s_waitcnt lgkmcnt(4)
	v_pk_fma_f32 v[144:145], v[150:151], v[232:233], v[148:149] op_sel_hi:[0,1,1] neg_lo:[1,0,0] neg_hi:[1,0,0]
	ds_read_b128 v[224:227], v1 offset:48048
	ds_read_b128 v[240:243], v1 offset:48064
	v_pk_fma_f32 v[146:147], v[150:151], v[234:235], v[182:183] op_sel_hi:[0,1,1] neg_lo:[1,0,0] neg_hi:[1,0,0]
	s_waitcnt lgkmcnt(5)
	v_pk_fma_f32 v[148:149], v[138:139], v[228:229], v[152:153] op_sel:[1,0,0] neg_lo:[1,0,0] neg_hi:[1,0,0]
	s_waitcnt lgkmcnt(3)
	v_pk_fma_f32 v[144:145], v[138:139], v[244:245], v[144:145] op_sel:[1,0,0] neg_lo:[1,0,0] neg_hi:[1,0,0]
	ds_read_b128 v[232:235], v1 offset:48176
	v_pk_fma_f32 v[150:151], v[138:139], v[230:231], v[154:155] op_sel:[1,0,0] neg_lo:[1,0,0] neg_hi:[1,0,0]
	v_pk_fma_f32 v[152:153], v[138:139], v[220:221], v[156:157] op_sel:[1,0,0] neg_lo:[1,0,0] neg_hi:[1,0,0]
	v_pk_fma_f32 v[154:155], v[138:139], v[222:223], v[158:159] op_sel:[1,0,0] neg_lo:[1,0,0] neg_hi:[1,0,0]
	ds_read_b128 v[220:223], v1 offset:48192
	ds_read_b128 v[228:231], v1 offset:48208
	v_pk_fma_f32 v[146:147], v[138:139], v[246:247], v[146:147] op_sel:[1,0,0] neg_lo:[1,0,0] neg_hi:[1,0,0]
	s_waitcnt lgkmcnt(5)
	v_pk_fma_f32 v[156:157], v[148:149], v[236:237], v[148:149] op_sel_hi:[0,1,1] neg_lo:[1,0,0] neg_hi:[1,0,0]
	s_waitcnt lgkmcnt(3)
	v_pk_fma_f32 v[144:145], v[148:149], v[240:241], v[144:145] op_sel_hi:[0,1,1] neg_lo:[1,0,0] neg_hi:[1,0,0]
	ds_read_b128 v[244:247], v1 offset:48320
	v_pk_fma_f32 v[150:151], v[148:149], v[238:239], v[150:151] op_sel_hi:[0,1,1] neg_lo:[1,0,0] neg_hi:[1,0,0]
	v_pk_fma_f32 v[152:153], v[148:149], v[224:225], v[152:153] op_sel_hi:[0,1,1] neg_lo:[1,0,0] neg_hi:[1,0,0]
	ds_read_b128 v[236:239], v1 offset:48336
	v_pk_fma_f32 v[154:155], v[148:149], v[226:227], v[154:155] op_sel_hi:[0,1,1] neg_lo:[1,0,0] neg_hi:[1,0,0]
	v_pk_fma_f32 v[146:147], v[148:149], v[242:243], v[146:147] op_sel_hi:[0,1,1] neg_lo:[1,0,0] neg_hi:[1,0,0]
	ds_read_b128 v[224:227], v1 offset:48352
	s_waitcnt lgkmcnt(5)
	v_pk_fma_f32 v[148:149], v[156:157], v[232:233], v[156:157] op_sel:[1,0,0] neg_lo:[1,0,0] neg_hi:[1,0,0]
	v_pk_fma_f32 v[150:151], v[156:157], v[234:235], v[150:151] op_sel:[1,0,0] neg_lo:[1,0,0] neg_hi:[1,0,0]
	ds_read_b128 v[232:235], v1 offset:48480
	s_waitcnt lgkmcnt(4)
	v_pk_fma_f32 v[158:159], v[156:157], v[228:229], v[144:145] op_sel:[1,0,0] neg_lo:[1,0,0] neg_hi:[1,0,0]
	ds_read_b128 v[240:243], v1 offset:48496
	v_pk_fma_f32 v[152:153], v[156:157], v[220:221], v[152:153] op_sel:[1,0,0] neg_lo:[1,0,0] neg_hi:[1,0,0]
	v_pk_fma_f32 v[154:155], v[156:157], v[222:223], v[154:155] op_sel:[1,0,0] neg_lo:[1,0,0] neg_hi:[1,0,0]
	v_pk_fma_f32 v[156:157], v[156:157], v[230:231], v[146:147] op_sel:[1,0,0] neg_lo:[1,0,0] neg_hi:[1,0,0]
	ds_read_b128 v[220:223], v1 offset:48624
	s_waitcnt lgkmcnt(5)
	v_pk_fma_f32 v[140:141], v[150:151], v[244:245], v[148:149] op_sel_hi:[0,1,1] neg_lo:[1,0,0] neg_hi:[1,0,0]
	ds_read_b128 v[228:231], v1 offset:48640
	v_pk_fma_f32 v[142:143], v[150:151], v[246:247], v[150:151] op_sel_hi:[0,1,1] neg_lo:[1,0,0] neg_hi:[1,0,0]
	s_waitcnt lgkmcnt(5)
	v_pk_fma_f32 v[148:149], v[150:151], v[236:237], v[152:153] op_sel_hi:[0,1,1] neg_lo:[1,0,0] neg_hi:[1,0,0]
	v_pk_fma_f32 v[152:153], v[150:151], v[238:239], v[154:155] op_sel_hi:[0,1,1] neg_lo:[1,0,0] neg_hi:[1,0,0]
	ds_read_b128 v[236:239], v1 offset:48768
	s_waitcnt lgkmcnt(5)
	v_pk_fma_f32 v[144:145], v[150:151], v[224:225], v[158:159] op_sel_hi:[0,1,1] neg_lo:[1,0,0] neg_hi:[1,0,0]
	v_pk_fma_f32 v[146:147], v[150:151], v[226:227], v[156:157] op_sel_hi:[0,1,1] neg_lo:[1,0,0] neg_hi:[1,0,0]
	ds_read_b128 v[224:227], v1 offset:48784
	s_waitcnt lgkmcnt(5)
	v_pk_fma_f32 v[148:149], v[142:143], v[232:233], v[148:149] op_sel:[1,0,0] neg_lo:[1,0,0] neg_hi:[1,0,0]
	s_waitcnt lgkmcnt(4)
	v_pk_fma_f32 v[144:145], v[142:143], v[240:241], v[144:145] op_sel:[1,0,0] neg_lo:[1,0,0] neg_hi:[1,0,0]
	ds_read_b128 v[244:247], v1 offset:48912
	v_pk_fma_f32 v[150:151], v[142:143], v[234:235], v[152:153] op_sel:[1,0,0] neg_lo:[1,0,0] neg_hi:[1,0,0]
	v_pk_fma_f32 v[146:147], v[142:143], v[242:243], v[146:147] op_sel:[1,0,0] neg_lo:[1,0,0] neg_hi:[1,0,0]
	ds_read_b128 v[232:235], v1 offset:48928
	s_waitcnt lgkmcnt(5)
	v_pk_fma_f32 v[152:153], v[148:149], v[220:221], v[148:149] op_sel_hi:[0,1,1] neg_lo:[1,0,0] neg_hi:[1,0,0]
	s_waitcnt lgkmcnt(4)
	v_pk_fma_f32 v[144:145], v[148:149], v[228:229], v[144:145] op_sel_hi:[0,1,1] neg_lo:[1,0,0] neg_hi:[1,0,0]
	ds_read_b128 v[240:243], v1 offset:49072
	v_pk_fma_f32 v[150:151], v[148:149], v[222:223], v[150:151] op_sel_hi:[0,1,1] neg_lo:[1,0,0] neg_hi:[1,0,0]
	v_pk_fma_f32 v[146:147], v[148:149], v[230:231], v[146:147] op_sel_hi:[0,1,1] neg_lo:[1,0,0] neg_hi:[1,0,0]
	ds_read_b128 v[220:223], v1 offset:49216
	s_waitcnt lgkmcnt(5)
	v_pk_fma_f32 v[148:149], v[152:153], v[236:237], v[152:153] op_sel:[1,0,0] neg_lo:[1,0,0] neg_hi:[1,0,0]
	v_pk_fma_f32 v[154:155], v[152:153], v[238:239], v[150:151] op_sel:[1,0,0] neg_lo:[1,0,0] neg_hi:[1,0,0]
	ds_read_b128 v[228:231], v1 offset:49360
	s_waitcnt lgkmcnt(5)
	v_pk_fma_f32 v[144:145], v[152:153], v[224:225], v[144:145] op_sel:[1,0,0] neg_lo:[1,0,0] neg_hi:[1,0,0]
	v_pk_fma_f32 v[146:147], v[152:153], v[226:227], v[146:147] op_sel:[1,0,0] neg_lo:[1,0,0] neg_hi:[1,0,0]
	ds_read_b128 v[224:227], v1 offset:49504
	s_waitcnt lgkmcnt(5)
	v_pk_fma_f32 v[148:149], v[154:155], v[244:245], v[148:149] op_sel_hi:[0,1,1] neg_lo:[1,0,0] neg_hi:[1,0,0]
	v_pk_fma_f32 v[150:151], v[154:155], v[246:247], v[154:155] op_sel_hi:[0,1,1] neg_lo:[1,0,0] neg_hi:[1,0,0]
	s_waitcnt lgkmcnt(4)
	v_pk_fma_f32 v[64:65], v[154:155], v[232:233], v[144:145] op_sel_hi:[0,1,1] neg_lo:[1,0,0] neg_hi:[1,0,0]
	v_pk_fma_f32 v[66:67], v[154:155], v[234:235], v[146:147] op_sel_hi:[0,1,1] neg_lo:[1,0,0] neg_hi:[1,0,0]
	s_waitcnt lgkmcnt(3)
	v_pk_fma_f32 v[64:65], v[150:151], v[240:241], v[64:65] op_sel:[1,0,0] neg_lo:[1,0,0] neg_hi:[1,0,0]
	v_pk_fma_f32 v[66:67], v[150:151], v[242:243], v[66:67] op_sel:[1,0,0] neg_lo:[1,0,0] neg_hi:[1,0,0]
	s_waitcnt lgkmcnt(2)
	v_pk_fma_f32 v[144:145], v[64:65], v[220:221], v[64:65] op_sel_hi:[0,1,1] neg_lo:[1,0,0] neg_hi:[1,0,0]
	v_pk_fma_f32 v[64:65], v[64:65], v[222:223], v[66:67] op_sel_hi:[0,1,1] neg_lo:[1,0,0] neg_hi:[1,0,0]
	s_waitcnt lgkmcnt(1)
	v_pk_fma_f32 v[66:67], v[144:145], v[228:229], v[144:145] op_sel:[1,0,0] neg_lo:[1,0,0] neg_hi:[1,0,0]
	v_pk_fma_f32 v[64:65], v[144:145], v[230:231], v[64:65] op_sel:[1,0,0] neg_lo:[1,0,0] neg_hi:[1,0,0]
	s_waitcnt lgkmcnt(0)
	v_pk_fma_f32 v[144:145], v[64:65], v[224:225], v[66:67] op_sel_hi:[0,1,1] neg_lo:[1,0,0] neg_hi:[1,0,0]
	v_pk_fma_f32 v[146:147], v[64:65], v[226:227], v[64:65] op_sel_hi:[0,1,1] neg_lo:[1,0,0] neg_hi:[1,0,0]
	s_or_b64 exec, exec, s[2:3]
	s_and_saveexec_b64 s[2:3], s[14:15]
	s_xor_b64 s[2:3], exec, s[2:3]
	s_cbranch_execz .LBB0_600
